# phase 1 big tiles: 48 of 64 MFMAs before the second barrier and DMA issue, per-fragment lgkmcnt waits
# baseline (speedup 1.0000x reference)
.Lbig_k_in:
	s_barrier
	ds_read_b128 v[160:163], v198 offset:0
	ds_read_b128 v[164:167], v198 offset:2048
	ds_read_b128 v[168:171], v198 offset:4096
	ds_read_b128 v[172:175], v198 offset:6144
	ds_read_b128 v[128:131], v196 offset:0
	ds_read_b128 v[132:135], v196 offset:2048
	ds_read_b128 v[136:139], v196 offset:4096
	ds_read_b128 v[140:143], v196 offset:6144
	ds_read_b128 v[144:147], v196 offset:8192
	ds_read_b128 v[148:151], v196 offset:10240
	ds_read_b128 v[152:155], v196 offset:12288
	ds_read_b128 v[156:159], v196 offset:14336
	ds_read_b128 v[176:179], v200 offset:0
	ds_read_b128 v[180:183], v200 offset:2048
	ds_read_b128 v[184:187], v200 offset:4096
	ds_read_b128 v[188:191], v200 offset:6144
	ds_read_b128 v[204:207], v197 offset:0
	ds_read_b128 v[208:211], v197 offset:2048
	ds_read_b128 v[212:215], v197 offset:4096
	ds_read_b128 v[216:219], v197 offset:6144
	ds_read_b128 v[220:223], v197 offset:8192
	ds_read_b128 v[224:227], v197 offset:10240
	ds_read_b128 v[228:231], v197 offset:12288
	ds_read_b128 v[232:235], v197 offset:14336
	s_setprio 1
	s_waitcnt lgkmcnt(15)
	v_mfma_f32_16x16x32_bf16 v[0:3], v[160:163], v[128:131], v[0:3]
	v_mfma_f32_16x16x32_bf16 v[4:7], v[164:167], v[128:131], v[4:7]
	v_mfma_f32_16x16x32_bf16 v[8:11], v[168:171], v[128:131], v[8:11]
	v_mfma_f32_16x16x32_bf16 v[12:15], v[172:175], v[128:131], v[12:15]
	s_waitcnt lgkmcnt(15)
	v_mfma_f32_16x16x32_bf16 v[16:19], v[160:163], v[132:135], v[16:19]
	v_mfma_f32_16x16x32_bf16 v[20:23], v[164:167], v[132:135], v[20:23]
	v_mfma_f32_16x16x32_bf16 v[24:27], v[168:171], v[132:135], v[24:27]
	v_mfma_f32_16x16x32_bf16 v[28:31], v[172:175], v[132:135], v[28:31]
	s_waitcnt lgkmcnt(15)
	v_mfma_f32_16x16x32_bf16 v[32:35], v[160:163], v[136:139], v[32:35]
	v_mfma_f32_16x16x32_bf16 v[36:39], v[164:167], v[136:139], v[36:39]
	v_mfma_f32_16x16x32_bf16 v[40:43], v[168:171], v[136:139], v[40:43]
	v_mfma_f32_16x16x32_bf16 v[44:47], v[172:175], v[136:139], v[44:47]
	s_waitcnt lgkmcnt(15)
	v_mfma_f32_16x16x32_bf16 v[48:51], v[160:163], v[140:143], v[48:51]
	v_mfma_f32_16x16x32_bf16 v[52:55], v[164:167], v[140:143], v[52:55]
	v_mfma_f32_16x16x32_bf16 v[56:59], v[168:171], v[140:143], v[56:59]
	v_mfma_f32_16x16x32_bf16 v[60:63], v[172:175], v[140:143], v[60:63]
	s_waitcnt lgkmcnt(15)
	v_mfma_f32_16x16x32_bf16 v[64:67], v[160:163], v[144:147], v[64:67]
	v_mfma_f32_16x16x32_bf16 v[68:71], v[164:167], v[144:147], v[68:71]
	v_mfma_f32_16x16x32_bf16 v[72:75], v[168:171], v[144:147], v[72:75]
	v_mfma_f32_16x16x32_bf16 v[76:79], v[172:175], v[144:147], v[76:79]
	s_waitcnt lgkmcnt(14)
	v_mfma_f32_16x16x32_bf16 v[80:83], v[160:163], v[148:151], v[80:83]
	v_mfma_f32_16x16x32_bf16 v[84:87], v[164:167], v[148:151], v[84:87]
	v_mfma_f32_16x16x32_bf16 v[88:91], v[168:171], v[148:151], v[88:91]
	v_mfma_f32_16x16x32_bf16 v[92:95], v[172:175], v[148:151], v[92:95]
	s_waitcnt lgkmcnt(13)
	v_mfma_f32_16x16x32_bf16 v[96:99], v[160:163], v[152:155], v[96:99]
	v_mfma_f32_16x16x32_bf16 v[100:103], v[164:167], v[152:155], v[100:103]
	v_mfma_f32_16x16x32_bf16 v[104:107], v[168:171], v[152:155], v[104:107]
	v_mfma_f32_16x16x32_bf16 v[108:111], v[172:175], v[152:155], v[108:111]
	s_waitcnt lgkmcnt(12)
	v_mfma_f32_16x16x32_bf16 v[112:115], v[160:163], v[156:159], v[112:115]
	v_mfma_f32_16x16x32_bf16 v[116:119], v[164:167], v[156:159], v[116:119]
	v_mfma_f32_16x16x32_bf16 v[120:123], v[168:171], v[156:159], v[120:123]
	v_mfma_f32_16x16x32_bf16 v[124:127], v[172:175], v[156:159], v[124:127]
	s_waitcnt lgkmcnt(7)
	v_mfma_f32_16x16x32_bf16 v[0:3], v[176:179], v[204:207], v[0:3]
	v_mfma_f32_16x16x32_bf16 v[4:7], v[180:183], v[204:207], v[4:7]
	v_mfma_f32_16x16x32_bf16 v[8:11], v[184:187], v[204:207], v[8:11]
	v_mfma_f32_16x16x32_bf16 v[12:15], v[188:191], v[204:207], v[12:15]
	s_waitcnt lgkmcnt(6)
	v_mfma_f32_16x16x32_bf16 v[16:19], v[176:179], v[208:211], v[16:19]
	v_mfma_f32_16x16x32_bf16 v[20:23], v[180:183], v[208:211], v[20:23]
	v_mfma_f32_16x16x32_bf16 v[24:27], v[184:187], v[208:211], v[24:27]
	v_mfma_f32_16x16x32_bf16 v[28:31], v[188:191], v[208:211], v[28:31]
	s_waitcnt lgkmcnt(5)
	v_mfma_f32_16x16x32_bf16 v[32:35], v[176:179], v[212:215], v[32:35]
	v_mfma_f32_16x16x32_bf16 v[36:39], v[180:183], v[212:215], v[36:39]
	v_mfma_f32_16x16x32_bf16 v[40:43], v[184:187], v[212:215], v[40:43]
	v_mfma_f32_16x16x32_bf16 v[44:47], v[188:191], v[212:215], v[44:47]
	s_waitcnt lgkmcnt(4)
	v_mfma_f32_16x16x32_bf16 v[48:51], v[176:179], v[216:219], v[48:51]
	v_mfma_f32_16x16x32_bf16 v[52:55], v[180:183], v[216:219], v[52:55]
	v_mfma_f32_16x16x32_bf16 v[56:59], v[184:187], v[216:219], v[56:59]
	v_mfma_f32_16x16x32_bf16 v[60:63], v[188:191], v[216:219], v[60:63]
	s_setprio 0
	s_waitcnt lgkmcnt(0)
	s_barrier
	s_add_u32 m0, s32, 0x0
	s_nop 0
	global_load_lds_dwordx4 v192, s[36:37]
	s_add_u32 m0, s32, 0x1000
	s_nop 0
	global_load_lds_dwordx4 v193, s[36:37]
	s_add_u32 m0, s32, 0x2000
	s_nop 0
	global_load_lds_dwordx4 v194, s[36:37]
	s_add_u32 m0, s32, 0x3000
	s_nop 0
	global_load_lds_dwordx4 v195, s[36:37]
	s_add_u32 m0, s32, 0x4000
	s_nop 0
	global_load_lds_dwordx4 v192, s[40:41]
	s_add_u32 m0, s32, 0x5000
	s_nop 0
	global_load_lds_dwordx4 v193, s[40:41]
	s_add_u32 m0, s32, 0x6000
	s_nop 0
	global_load_lds_dwordx4 v194, s[40:41]
	s_add_u32 m0, s32, 0x7000
	s_nop 0
	global_load_lds_dwordx4 v195, s[40:41]
	s_add_u32 m0, s32, 0x8000
	s_nop 0
	global_load_lds_dwordx4 v192, s[44:45]
	s_add_u32 m0, s32, 0x9000
	s_nop 0
	global_load_lds_dwordx4 v193, s[44:45]
	s_add_u32 m0, s32, 0xa000
	s_nop 0
	global_load_lds_dwordx4 v194, s[44:45]
	s_add_u32 m0, s32, 0xb000
	s_nop 0
	global_load_lds_dwordx4 v195, s[44:45]
	s_add_u32 s36, s36, 0x80
	s_addc_u32 s37, s37, 0
	s_add_u32 s40, s40, 0x80
	s_addc_u32 s41, s41, 0
	s_add_u32 s44, s44, 0x80
	s_addc_u32 s45, s45, 0
	s_add_i32 s20, s20, 1
	s_cmp_eq_u32 s20, 32
	s_cbranch_scc1 .Lbig_wrap1
.Lbig_wrapret1:
	s_setprio 1
	v_mfma_f32_16x16x32_bf16 v[64:67], v[176:179], v[220:223], v[64:67]
	v_mfma_f32_16x16x32_bf16 v[68:71], v[180:183], v[220:223], v[68:71]
	v_mfma_f32_16x16x32_bf16 v[72:75], v[184:187], v[220:223], v[72:75]
	v_mfma_f32_16x16x32_bf16 v[76:79], v[188:191], v[220:223], v[76:79]
	v_mfma_f32_16x16x32_bf16 v[80:83], v[176:179], v[224:227], v[80:83]
	v_mfma_f32_16x16x32_bf16 v[84:87], v[180:183], v[224:227], v[84:87]
	v_mfma_f32_16x16x32_bf16 v[88:91], v[184:187], v[224:227], v[88:91]
	v_mfma_f32_16x16x32_bf16 v[92:95], v[188:191], v[224:227], v[92:95]
	v_mfma_f32_16x16x32_bf16 v[96:99], v[176:179], v[228:231], v[96:99]
	v_mfma_f32_16x16x32_bf16 v[100:103], v[180:183], v[228:231], v[100:103]
	v_mfma_f32_16x16x32_bf16 v[104:107], v[184:187], v[228:231], v[104:107]
	v_mfma_f32_16x16x32_bf16 v[108:111], v[188:191], v[228:231], v[108:111]
	v_mfma_f32_16x16x32_bf16 v[112:115], v[176:179], v[232:235], v[112:115]
	v_mfma_f32_16x16x32_bf16 v[116:119], v[180:183], v[232:235], v[116:119]
	v_mfma_f32_16x16x32_bf16 v[120:123], v[184:187], v[232:235], v[120:123]
	v_mfma_f32_16x16x32_bf16 v[124:127], v[188:191], v[232:235], v[124:127]
	s_setprio 0
	s_add_i32 s50, s50, 1
	s_cmp_lt_u32 s50, 31
	s_cbranch_scc1 .Lbig_k
	s_waitcnt vmcnt(0)
	s_barrier
	ds_read_b128 v[160:163], v198 offset:0
	ds_read_b128 v[164:167], v198 offset:2048
	ds_read_b128 v[168:171], v198 offset:4096
	ds_read_b128 v[172:175], v198 offset:6144
	ds_read_b128 v[128:131], v196 offset:0
	ds_read_b128 v[132:135], v196 offset:2048
	ds_read_b128 v[136:139], v196 offset:4096
	ds_read_b128 v[140:143], v196 offset:6144
	ds_read_b128 v[144:147], v196 offset:8192
	ds_read_b128 v[148:151], v196 offset:10240
	ds_read_b128 v[152:155], v196 offset:12288
	ds_read_b128 v[156:159], v196 offset:14336
	ds_read_b128 v[176:179], v200 offset:0
	ds_read_b128 v[180:183], v200 offset:2048
	ds_read_b128 v[184:187], v200 offset:4096
	ds_read_b128 v[188:191], v200 offset:6144
	ds_read_b128 v[204:207], v197 offset:0
	ds_read_b128 v[208:211], v197 offset:2048
	ds_read_b128 v[212:215], v197 offset:4096
	ds_read_b128 v[216:219], v197 offset:6144
	ds_read_b128 v[220:223], v197 offset:8192
	ds_read_b128 v[224:227], v197 offset:10240
	ds_read_b128 v[228:231], v197 offset:12288
	ds_read_b128 v[232:235], v197 offset:14336
	s_setprio 1
	s_waitcnt lgkmcnt(15)
	v_mfma_f32_16x16x32_bf16 v[0:3], v[160:163], v[128:131], v[0:3]
	v_mfma_f32_16x16x32_bf16 v[4:7], v[164:167], v[128:131], v[4:7]
	v_mfma_f32_16x16x32_bf16 v[8:11], v[168:171], v[128:131], v[8:11]
	v_mfma_f32_16x16x32_bf16 v[12:15], v[172:175], v[128:131], v[12:15]
	s_waitcnt lgkmcnt(15)
	v_mfma_f32_16x16x32_bf16 v[16:19], v[160:163], v[132:135], v[16:19]
	v_mfma_f32_16x16x32_bf16 v[20:23], v[164:167], v[132:135], v[20:23]
	v_mfma_f32_16x16x32_bf16 v[24:27], v[168:171], v[132:135], v[24:27]
	v_mfma_f32_16x16x32_bf16 v[28:31], v[172:175], v[132:135], v[28:31]
	s_waitcnt lgkmcnt(15)
	v_mfma_f32_16x16x32_bf16 v[32:35], v[160:163], v[136:139], v[32:35]
	v_mfma_f32_16x16x32_bf16 v[36:39], v[164:167], v[136:139], v[36:39]
	v_mfma_f32_16x16x32_bf16 v[40:43], v[168:171], v[136:139], v[40:43]
	v_mfma_f32_16x16x32_bf16 v[44:47], v[172:175], v[136:139], v[44:47]
	s_waitcnt lgkmcnt(15)
	v_mfma_f32_16x16x32_bf16 v[48:51], v[160:163], v[140:143], v[48:51]
	v_mfma_f32_16x16x32_bf16 v[52:55], v[164:167], v[140:143], v[52:55]
	v_mfma_f32_16x16x32_bf16 v[56:59], v[168:171], v[140:143], v[56:59]
	v_mfma_f32_16x16x32_bf16 v[60:63], v[172:175], v[140:143], v[60:63]
	s_waitcnt lgkmcnt(15)
	v_mfma_f32_16x16x32_bf16 v[64:67], v[160:163], v[144:147], v[64:67]
	v_mfma_f32_16x16x32_bf16 v[68:71], v[164:167], v[144:147], v[68:71]
	v_mfma_f32_16x16x32_bf16 v[72:75], v[168:171], v[144:147], v[72:75]
	v_mfma_f32_16x16x32_bf16 v[76:79], v[172:175], v[144:147], v[76:79]
	s_waitcnt lgkmcnt(14)
	v_mfma_f32_16x16x32_bf16 v[80:83], v[160:163], v[148:151], v[80:83]
	v_mfma_f32_16x16x32_bf16 v[84:87], v[164:167], v[148:151], v[84:87]
	v_mfma_f32_16x16x32_bf16 v[88:91], v[168:171], v[148:151], v[88:91]
	v_mfma_f32_16x16x32_bf16 v[92:95], v[172:175], v[148:151], v[92:95]
	s_waitcnt lgkmcnt(13)
	v_mfma_f32_16x16x32_bf16 v[96:99], v[160:163], v[152:155], v[96:99]
	v_mfma_f32_16x16x32_bf16 v[100:103], v[164:167], v[152:155], v[100:103]
	v_mfma_f32_16x16x32_bf16 v[104:107], v[168:171], v[152:155], v[104:107]
	v_mfma_f32_16x16x32_bf16 v[108:111], v[172:175], v[152:155], v[108:111]
	s_waitcnt lgkmcnt(12)
	v_mfma_f32_16x16x32_bf16 v[112:115], v[160:163], v[156:159], v[112:115]
	v_mfma_f32_16x16x32_bf16 v[116:119], v[164:167], v[156:159], v[116:119]
	v_mfma_f32_16x16x32_bf16 v[120:123], v[168:171], v[156:159], v[120:123]
	v_mfma_f32_16x16x32_bf16 v[124:127], v[172:175], v[156:159], v[124:127]
	s_waitcnt lgkmcnt(7)
	v_mfma_f32_16x16x32_bf16 v[0:3], v[176:179], v[204:207], v[0:3]
	v_mfma_f32_16x16x32_bf16 v[4:7], v[180:183], v[204:207], v[4:7]
	v_mfma_f32_16x16x32_bf16 v[8:11], v[184:187], v[204:207], v[8:11]
	v_mfma_f32_16x16x32_bf16 v[12:15], v[188:191], v[204:207], v[12:15]
	s_waitcnt lgkmcnt(6)
	v_mfma_f32_16x16x32_bf16 v[16:19], v[176:179], v[208:211], v[16:19]
	v_mfma_f32_16x16x32_bf16 v[20:23], v[180:183], v[208:211], v[20:23]
	v_mfma_f32_16x16x32_bf16 v[24:27], v[184:187], v[208:211], v[24:27]
	v_mfma_f32_16x16x32_bf16 v[28:31], v[188:191], v[208:211], v[28:31]
	s_waitcnt lgkmcnt(5)
	v_mfma_f32_16x16x32_bf16 v[32:35], v[176:179], v[212:215], v[32:35]
	v_mfma_f32_16x16x32_bf16 v[36:39], v[180:183], v[212:215], v[36:39]
	v_mfma_f32_16x16x32_bf16 v[40:43], v[184:187], v[212:215], v[40:43]
	v_mfma_f32_16x16x32_bf16 v[44:47], v[188:191], v[212:215], v[44:47]
	s_waitcnt lgkmcnt(4)
	v_mfma_f32_16x16x32_bf16 v[48:51], v[176:179], v[216:219], v[48:51]
	v_mfma_f32_16x16x32_bf16 v[52:55], v[180:183], v[216:219], v[52:55]
	v_mfma_f32_16x16x32_bf16 v[56:59], v[184:187], v[216:219], v[56:59]
	v_mfma_f32_16x16x32_bf16 v[60:63], v[188:191], v[216:219], v[60:63]
	s_setprio 0
	s_waitcnt lgkmcnt(0)
	s_cmp_ge_u32 s91, 0x1400
	s_cbranch_scc1 .Lbig_nonext
	s_barrier
	s_mov_b64 s[36:37], s[46:47]
	s_mov_b64 s[44:45], s[48:49]
	s_add_u32 s40, s36, 0x80000
	s_addc_u32 s41, s37, 0
	s_mov_b32 s20, s21
	s_add_u32 m0, s32, 0x0
	s_nop 0
	global_load_lds_dwordx4 v192, s[36:37]
	s_add_u32 m0, s32, 0x1000
	s_nop 0
	global_load_lds_dwordx4 v193, s[36:37]
	s_add_u32 m0, s32, 0x2000
	s_nop 0
	global_load_lds_dwordx4 v194, s[36:37]
	s_add_u32 m0, s32, 0x3000
	s_nop 0
	global_load_lds_dwordx4 v195, s[36:37]
	s_add_u32 m0, s32, 0x4000
	s_nop 0
	global_load_lds_dwordx4 v192, s[40:41]
	s_add_u32 m0, s32, 0x5000
	s_nop 0
	global_load_lds_dwordx4 v193, s[40:41]
	s_add_u32 m0, s32, 0x6000
	s_nop 0
	global_load_lds_dwordx4 v194, s[40:41]
	s_add_u32 m0, s32, 0x7000
	s_nop 0
	global_load_lds_dwordx4 v195, s[40:41]
	s_add_u32 m0, s32, 0x8000
	s_nop 0
	global_load_lds_dwordx4 v192, s[44:45]
	s_add_u32 m0, s32, 0x9000
	s_nop 0
	global_load_lds_dwordx4 v193, s[44:45]
	s_add_u32 m0, s32, 0xa000
	s_nop 0
	global_load_lds_dwordx4 v194, s[44:45]
	s_add_u32 m0, s32, 0xb000
	s_nop 0
	global_load_lds_dwordx4 v195, s[44:45]
	s_add_u32 s36, s36, 0x80
	s_addc_u32 s37, s37, 0
	s_add_u32 s40, s40, 0x80
	s_addc_u32 s41, s41, 0
	s_add_u32 s44, s44, 0x80
	s_addc_u32 s45, s45, 0
	s_add_i32 s20, s20, 1
	s_cmp_eq_u32 s20, 32
	s_cbranch_scc1 .Lbig_wrap2
.Lbig_wrapret2:
.Lbig_nonext:
	s_setprio 1
	v_mfma_f32_16x16x32_bf16 v[64:67], v[176:179], v[220:223], v[64:67]
	v_mfma_f32_16x16x32_bf16 v[68:71], v[180:183], v[220:223], v[68:71]
	v_mfma_f32_16x16x32_bf16 v[72:75], v[184:187], v[220:223], v[72:75]
	v_mfma_f32_16x16x32_bf16 v[76:79], v[188:191], v[220:223], v[76:79]
	v_mfma_f32_16x16x32_bf16 v[80:83], v[176:179], v[224:227], v[80:83]
	v_mfma_f32_16x16x32_bf16 v[84:87], v[180:183], v[224:227], v[84:87]
	v_mfma_f32_16x16x32_bf16 v[88:91], v[184:187], v[224:227], v[88:91]
	v_mfma_f32_16x16x32_bf16 v[92:95], v[188:191], v[224:227], v[92:95]
	v_mfma_f32_16x16x32_bf16 v[96:99], v[176:179], v[228:231], v[96:99]
	v_mfma_f32_16x16x32_bf16 v[100:103], v[180:183], v[228:231], v[100:103]
	v_mfma_f32_16x16x32_bf16 v[104:107], v[184:187], v[228:231], v[104:107]
	v_mfma_f32_16x16x32_bf16 v[108:111], v[188:191], v[228:231], v[108:111]
	v_mfma_f32_16x16x32_bf16 v[112:115], v[176:179], v[232:235], v[112:115]
	v_mfma_f32_16x16x32_bf16 v[116:119], v[180:183], v[232:235], v[116:119]
	v_mfma_f32_16x16x32_bf16 v[120:123], v[184:187], v[232:235], v[120:123]
	v_mfma_f32_16x16x32_bf16 v[124:127], v[188:191], v[232:235], v[124:127]
	s_setprio 0
	s_lshr_b32 s51, s90, 6
	s_lshl_b32 s51, s51, 7
	s_and_b32 s17, s90, 63
	s_lshl_b32 s17, s17, 8
	s_mov_b32 s16, 0x1b00
	s_mov_b32 s18, 0
	s_mov_b32 s19, 0
	s_cmp_lt_u32 s51, 0xd80
	s_cbranch_scc1 .Lbig_reg
	s_mov_b32 s16, 0x1900
	s_mov_b32 s18, 0x6c00000
	s_mov_b32 s19, 0xd80
	s_cmp_lt_u32 s51, 0x1a00
	s_cbranch_scc1 .Lbig_reg
	s_mov_b32 s16, 0x2000
	s_mov_b32 s18, 0xd000000
	s_mov_b32 s19, 0x1a00
